# v112 + in-proj GEMM column-sweep offset per XCD 11 instead of 5 (XCDs x and x+4 share a weight-column window)
# speedup vs baseline: 1.0022x; 1.0008x over previous
; #define LAS __attribute__((address_space(3)))
;     __device__ bool next(int i, Unit& u) const { const int tile = c + (i >> 2) * G; if (tile >= ntile) return false; u.pm = tile >> 2; u.pn = (i & 3) * 4 + (tile & 3); return true; }
;     __device__ bool next(int i, Unit& u) const {
;         const long L = (long)i * G + c; if (L >= nwg) return false;
;         int wgid = (int)L; { const int q = nwg / NXCD, r = nwg % NXCD, xcd = wgid % NXCD, off = wgid / NXCD; wgid = (xcd < r ? xcd * (q + 1) : r * (q + 1) + (xcd - r) * q) + off; }
;         const int nig = WGM * nN, gid = wgid / nig, fm = gid * WGM, gsz = (nM - fm) < WGM ? (nM - fm) : WGM;
;         u.pm = fm + ((wgid % nig) % gsz); u.pn = (wgid % nig) / gsz;
;         if (nN == 44) u.pn = (u.pn + 5 * (int)(L % NXCD)) % 44;
; __global__ __launch_bounds__(512, 2) void mega(Params p, int s0, int s1) {
;     extern __shared__ __attribute__((aligned(16))) unsigned char shm[];
;     LAS unsigned char* lds = (LAS unsigned char*)shm;
;     cg::grid_group grid = cg::this_grid();
;     volatile LAS unsigned* st = (volatile LAS unsigned*)(lds + XB_ST_OFF);
;     if (threadIdx.x == 0) { st[0] = 0u; st[1] = 0u; }
;     __syncthreads();
;     const XcdBarrier xb = xcd_barrier_post(p.bar, st);
.LBB0_5:
	s_or_b64 exec, exec, s[2:3]
	s_load_dwordx2 s[2:3], s[0:1], 0xe0
	s_waitcnt lgkmcnt(0)
	v_writelane_b32 v251, s2, 15
	s_nop 1
	v_writelane_b32 v251, s3, 16
	s_cmp_ge_i32 s2, s3
	s_cbranch_scc1 .Lnear_exit
	v_readlane_b32 s26, v251, 0
	s_cmpk_lt_i32 s26, 0x100
	s_cselect_b64 s[2:3], -1, 0
	s_load_dwordx16 s[44:59], s[0:1], 0x0
	s_load_dwordx16 s[4:19], s[0:1], 0x80
	v_writelane_b32 v251, s2, 17
	s_and_b32 s22, s26, 7
	s_lshl_b32 s22, s22, 5
	s_lshr_b32 s21, s26, 3
	s_add_i32 s21, s22, s21
	s_ashr_i32 s22, s21, 2
	s_and_b32 s21, s21, 3
	v_writelane_b32 v251, s3, 18
	s_mov_b32 s2, s22
	v_writelane_b32 v251, s2, 19
	s_ashr_i32 s23, s22, 31
	s_load_dwordx2 s[28:29], s[0:1], 0xe8
	v_writelane_b32 v251, s3, 20
	s_lshl_b64 s[2:3], s[22:23], 18
	v_writelane_b32 v251, s21, 21
	s_lshl_b32 s21, s21, 18
	s_waitcnt lgkmcnt(0)
	s_add_u32 s22, s6, s21
	s_addc_u32 s23, s7, 0
	s_add_u32 s2, s16, s2
	s_addc_u32 s3, s17, s3
	s_add_u32 s24, s22, 0x20000
	s_addc_u32 s25, s23, 0
	v_writelane_b32 v251, s24, 22
	s_load_dwordx8 s[36:43], s[0:1], 0xc0
	v_lshrrev_b32_e32 v1, 20, v0
	v_writelane_b32 v251, s25, 23
	s_add_u32 s24, s2, 0x20000
	v_writelane_b32 v251, s2, 24
	s_addc_u32 s25, s3, 0
	v_lshrrev_b32_e32 v0, 10, v0
	v_writelane_b32 v251, s3, 25
	v_writelane_b32 v251, s24, 26
	s_add_u32 s2, s22, 0x20080
	v_or_b32_e32 v0, v0, v1
	v_writelane_b32 v251, s25, 27
	v_writelane_b32 v251, s22, 28
	s_addc_u32 s3, s23, 0
	s_cmpk_lt_i32 s26, 0xb00
	v_writelane_b32 v251, s23, 29
	v_writelane_b32 v251, s2, 30
	s_movk_i32 s22, 0x161
	s_mov_b64 s[66:67], s[58:59]
	v_writelane_b32 v251, s3, 31
	s_cselect_b64 s[2:3], -1, 0
	v_writelane_b32 v251, s2, 32
	s_mov_b64 s[64:65], s[56:57]
	v_mbcnt_lo_u32_b32 v205, -1, 0
	v_writelane_b32 v251, s3, 33
	s_ashr_i32 s2, s26, 31
	v_writelane_b32 v251, s2, 34
	s_lshr_b32 s2, s2, 29
	s_add_i32 s2, s26, s2
	s_ashr_i32 s3, s2, 3
	s_and_b32 s2, s2, -8
	s_sub_i32 s2, s26, s2
	s_lshl_b32 s21, s2, 5
	s_cmp_lt_i32 s2, 0
	s_cselect_b32 s22, s22, 0x160
	s_mul_i32 s22, s22, s2
	s_mul_i32 s23, s2, 33
	s_cselect_b32 s24, s23, s21
	s_add_i32 s22, s22, s3
	s_mul_hi_i32 s21, s22, 0x2e8ba2e9
	s_lshr_b32 s23, s21, 31
	s_ashr_i32 s21, s21, 5
	s_add_i32 s21, s21, s23
	s_mul_i32 s23, s21, 0xb0
	s_sub_i32 s22, s22, s23
	s_bfe_u32 s23, s22, 0x2001d
	s_add_i32 s23, s22, s23
	s_sext_i32_i16 s25, s23
	s_and_b32 s23, s23, 0xfffc
	s_ashr_i32 s25, s25, 2
	s_sub_i32 s22, s22, s23
	s_mul_i32 s2, s2, 11
	s_lshl_b32 s21, s21, 2
	s_sext_i32_i16 s22, s22
	s_add_i32 s2, s2, s25
	s_add_i32 s30, s21, s22
	s_bfe_i32 s21, s2, 0x80000
	s_mul_i32 s21, s21, 47
	s_sext_i32_i16 s22, s21
	s_ashr_i32 s22, s22, 11
	s_bfe_u32 s21, s21, 0x1000f
	s_add_i32 s21, s22, s21
	s_mul_i32 s21, s21, 44
	s_sub_i32 s2, s2, s21
	s_ashr_i32 s21, s28, 31
	s_cmpk_lt_i32 s26, 0xf10
	v_writelane_b32 v251, s21, 35
	s_cselect_b64 s[22:23], -1, 0
	v_writelane_b32 v251, s22, 36
	s_cmp_lg_u64 s[58:59], 0
	v_mov_b32_e32 v1, 0
	v_writelane_b32 v251, s23, 37
	s_cselect_b64 s[22:23], -1, 0
	v_writelane_b32 v251, s22, 38
	s_lshl_b32 s21, s26, 3
	s_lshl_b32 s82, s28, 3
	v_writelane_b32 v251, s23, 39
	s_load_dwordx2 s[22:23], s[0:1], 0xe0
	v_writelane_b32 v251, s21, 40
	v_mov_b32_e32 v199, 0x358637bd
	v_mov_b32_e32 v200, 0x10001
	v_mov_b32_e32 v201, 0x3ecc95a3
	s_waitcnt lgkmcnt(0)
	s_cmp_gt_i32 s23, -1
	s_cselect_b64 s[22:23], -1, 0
	v_writelane_b32 v251, s22, 41
	v_mov_b32_e32 v202, 1
	v_mov_b32_e32 v203, 0x3b808081
	v_writelane_b32 v251, s23, 42
	s_add_u32 s22, s40, 0x200
	s_addc_u32 s23, s41, 0
	v_writelane_b32 v251, s22, 43
	v_mov_b32_e32 v204, 0xa00
	v_mbcnt_hi_u32_b32 v206, -1, v205
	v_writelane_b32 v251, s23, 44
	s_add_u32 s22, s40, 0x1000
	s_addc_u32 s23, s41, 0
	v_writelane_b32 v251, s22, 45
	v_mov_b32_e32 v207, 0xfff0fff
	v_mov_b32_e32 v208, 0xff800000
	v_writelane_b32 v251, s23, 46
	s_add_u32 s22, s40, 0x1100
	s_addc_u32 s23, s41, 0
	v_writelane_b32 v251, s22, 47
	v_mov_b32_e32 v162, 0x3f317218
	v_mov_b32_e32 v209, 0x7f800000
	v_writelane_b32 v251, s23, 48
	s_add_u32 s22, s40, 0x1200
	s_addc_u32 s23, s41, 0
	v_writelane_b32 v251, s22, 49
	v_mov_b32_e32 v210, 0x7fc00000
	v_mov_b64_e32 v[164:165], 0xaff
	v_writelane_b32 v251, s23, 50
	s_add_u32 s22, s40, 0x1300
	s_addc_u32 s23, s41, 0
	v_writelane_b32 v251, s22, 51
	s_cmp_eq_u32 s20, 15
	v_mov_b64_e32 v[166:167], 0xb00
	v_writelane_b32 v251, s23, 52
	s_cselect_b64 s[22:23], -1, 0
	v_writelane_b32 v251, s22, 53
	s_cmp_eq_u32 s20, 14
	v_mov_b64_e32 v[168:169], 0xff
	v_writelane_b32 v251, s23, 54
	s_cselect_b64 s[22:23], -1, 0
	v_writelane_b32 v251, s22, 55
	s_cmp_eq_u32 s20, 13
	v_mov_b64_e32 v[170:171], 0x100
	v_writelane_b32 v251, s23, 56
	s_cselect_b64 s[22:23], -1, 0
	v_writelane_b32 v251, s22, 57
	s_cmp_eq_u32 s20, 12
	s_movk_i32 s84, 0x2000
	v_writelane_b32 v251, s23, 58
	s_cselect_b64 s[22:23], -1, 0
	v_writelane_b32 v251, s22, 59
	s_cmp_eq_u32 s20, 11
	s_movk_i32 s33, 0x5800
	v_writelane_b32 v251, s23, 60
	s_cselect_b64 s[22:23], -1, 0
	v_writelane_b32 v251, s22, 61
	s_cmp_eq_u32 s20, 10
	s_mov_b32 s85, 0x800000
	v_writelane_b32 v251, s23, 62
	s_cselect_b64 s[22:23], -1, 0
	v_writelane_b32 v251, s22, 63
	s_cmp_eq_u32 s20, 9
	s_mov_b32 s86, 0xd000
	v_writelane_b32 v252, s23, 0
	s_cselect_b64 s[22:23], -1, 0
	v_writelane_b32 v252, s22, 1
	s_cmp_eq_u32 s20, 8
	s_movk_i32 s87, 0x204
	v_writelane_b32 v252, s23, 2
	s_cselect_b64 s[22:23], -1, 0
	v_writelane_b32 v252, s22, 3
	s_cmp_eq_u32 s20, 7
	s_mov_b64 s[90:91], 0x800
	v_writelane_b32 v252, s23, 4
	s_cselect_b64 s[22:23], -1, 0
	v_writelane_b32 v252, s22, 5
	s_cmp_eq_u32 s20, 6
	s_nop 0
	v_writelane_b32 v252, s23, 6
	s_cselect_b64 s[22:23], -1, 0
	v_writelane_b32 v252, s22, 7
	s_cmp_eq_u32 s20, 5
; #define LAS __attribute__((address_space(3)))
;     ...
;     else if (k == 1) { pg8::Gemm gm{p.hbuf, p.Wt, MG, NP, DM, 1 << 20, 0}; pg8::StaticOrder S; S.init(MG, NP, gridDim.x, blockIdx.x); EpiG1 E{p.proj, p.vT, p.kiP, p.gq}; pg8::gemm_phase(lds, gm, S, E); }
;     else if (k == 2) { step_mix(p, l, p.ctr + (l * NGRP + g) + 16 * rep, lds, rep ? REPT : 15, rep ? REPS : 63); }
;     else if (k == 3) { pg8::Gemm gm{p.ybuf, p.Wb, MG, 4096, 512, 4, (size_t)MG * 512 * 2}; pg8::BranchOrder S{(int)gridDim.x, (int)blockIdx.x, (MG / 256) * 4}; EpiG2 E{p.gq, p.hbuf}; pg8::gemm_phase(lds, gm, S, E); }
;     else { pg8::Gemm gm{p.hbuf, p.Wo, MG, DM, DM, 1 << 20, 0}; pg8::StaticOrder S; S.init(MG, DM, gridDim.x, blockIdx.x); EpiG3 E{(l == 0) ? p.x : p.out, rep ? (float*)p.proj - (size_t)g * MG * DM : p.out, g * MG}; pg8::gemm_phase(lds, gm, S, E); }
; }
; __global__ __launch_bounds__(512, 2) void mega(Params p, int s0, int s1) {
;     extern __shared__ __attribute__((aligned(16))) unsigned char shm[];
;     LAS unsigned char* lds = (LAS unsigned char*)shm;
;     cg::grid_group grid = cg::this_grid();
;     volatile LAS unsigned* st = (volatile LAS unsigned*)(lds + XB_ST_OFF);
;     if (threadIdx.x == 0) { st[0] = 0u; st[1] = 0u; }
;     __syncthreads();
;     const XcdBarrier xb = xcd_barrier_post(p.bar, st);
	s_nop 0
	v_writelane_b32 v252, s23, 8
	s_cselect_b64 s[22:23], -1, 0
	v_writelane_b32 v252, s22, 9
	s_cmp_eq_u32 s20, 4
	s_nop 0
	v_writelane_b32 v252, s23, 10
	s_cselect_b64 s[22:23], -1, 0
	v_writelane_b32 v252, s22, 11
	s_cmp_eq_u32 s20, 3
	s_nop 0
	v_writelane_b32 v252, s23, 12
	s_cselect_b64 s[22:23], -1, 0
	v_writelane_b32 v252, s22, 13
	s_cmp_eq_u32 s20, 2
	s_nop 0
	v_writelane_b32 v252, s23, 14
	s_cselect_b64 s[22:23], -1, 0
	v_writelane_b32 v252, s22, 15
	s_cmp_eq_u32 s20, 1
	s_nop 0
	v_writelane_b32 v252, s23, 16
	s_cselect_b64 s[22:23], -1, 0
	v_writelane_b32 v252, s22, 17
	s_cmp_eq_u32 s20, 0
	s_nop 0
	v_writelane_b32 v252, s23, 18
	s_cselect_b64 s[22:23], -1, 0
	s_lshl_b32 s20, s20, 8
	s_add_u32 s20, s40, s20
	v_writelane_b32 v252, s22, 19
	s_addc_u32 s21, s41, 0
	s_nop 0
	v_writelane_b32 v252, s23, 20
	s_add_u32 s22, s20, 0x1400
	s_addc_u32 s23, s21, 0
	v_writelane_b32 v252, s22, 21
	s_add_u32 s20, s20, 0x2400
	s_addc_u32 s21, s21, 0
	v_writelane_b32 v252, s23, 22
	v_writelane_b32 v252, s20, 23
	s_mov_b32 s22, s30
	s_nop 0
	v_writelane_b32 v252, s21, 24
	s_add_u32 s20, s40, 0x3400
	s_addc_u32 s21, s41, 0
	v_writelane_b32 v252, s20, 25
	s_nop 1
	v_writelane_b32 v252, s21, 26
	s_add_u32 s20, s40, 0x3500
	s_addc_u32 s21, s41, 0
	v_writelane_b32 v252, s20, 27
	s_ashr_i32 s31, s30, 31
	s_nop 0
	v_writelane_b32 v252, s21, 28
	s_bfe_i64 s[20:21], s[2:3], 0x80000
	v_writelane_b32 v252, s22, 29
	s_lshl_b64 s[20:21], s[20:21], 19
	s_sext_i32_i8 s2, s2
	v_writelane_b32 v252, s23, 30
	s_lshl_b64 s[22:23], s[30:31], 19
	s_add_u32 s20, s4, s20
	s_addc_u32 s21, s5, s21
	s_add_u32 s22, s12, s22
	s_addc_u32 s23, s13, s23
	s_add_u32 s30, s20, 0x40000
	s_addc_u32 s31, s21, 0
	v_writelane_b32 v252, s30, 31
	s_nop 1
	v_writelane_b32 v252, s31, 32
	s_add_u32 s30, s22, 0x40000
	v_writelane_b32 v252, s22, 33
	s_addc_u32 s31, s23, 0
	s_nop 0
	v_writelane_b32 v252, s23, 34
	v_writelane_b32 v252, s30, 35
	s_add_u32 s22, s20, 0x40080
	s_nop 0
	v_writelane_b32 v252, s31, 36
	v_writelane_b32 v252, s20, 37
	s_addc_u32 s23, s21, 0
	s_add_i32 s3, s24, s3
	v_writelane_b32 v252, s21, 38
	s_ashr_i32 s20, s3, 31
	s_lshr_b32 s20, s20, 28
	s_add_i32 s20, s3, s20
	s_and_b32 s21, s20, 0xfff0
	s_sub_i32 s3, s3, s21
	s_bfe_i32 s21, s3, 0x80000
	s_bfe_u32 s21, s21, 0x2000d
	v_writelane_b32 v252, s22, 39
	s_add_i32 s21, s3, s21
	s_ashr_i32 s20, s20, 4
	v_writelane_b32 v252, s23, 40
	s_and_b32 s22, s21, 0xfc
	s_sub_i32 s3, s3, s22
	s_bfe_i32 s21, s21, 0x80000
	s_lshl_b32 s20, s20, 2
	s_sext_i32_i16 s21, s21
	s_sext_i32_i8 s3, s3
	s_add_i32 s24, s20, s3
	s_ashr_i32 s3, s21, 2
	v_writelane_b32 v252, s3, 41
	s_lshr_b32 s20, s21, 2
	s_mov_b32 s22, s24
	s_load_dword s3, s[0:1], 0xf0
	s_ashr_i32 s25, s24, 31
	s_bfe_i64 s[20:21], s[20:21], 0x100000
	v_writelane_b32 v252, s22, 42
	s_lshl_b64 s[20:21], s[20:21], 19
	s_mov_b32 s31, 0
	v_writelane_b32 v252, s23, 43
	s_lshl_b64 s[22:23], s[24:25], 19
	s_add_u32 s20, s8, s20
	s_addc_u32 s21, s9, s21
	v_writelane_b32 v252, s2, 44
	s_mul_i32 s2, s29, s28
	s_add_u32 s22, s12, s22
	s_waitcnt lgkmcnt(0)
	s_mul_i32 s2, s2, s3
	s_addc_u32 s23, s13, s23
	v_writelane_b32 v252, s2, 45
	s_movk_i32 s2, 0x3ff
	v_and_or_b32 v0, v0, s2, v198
	s_add_u32 s2, s20, 0x40000
	s_addc_u32 s3, s21, 0
	v_writelane_b32 v252, s2, 46
	s_nop 1
	v_writelane_b32 v252, s3, 47
	s_add_u32 s2, s22, 0x40000
	v_writelane_b32 v252, s22, 48
	s_addc_u32 s3, s23, 0
	s_nop 0
	v_writelane_b32 v252, s23, 49
	v_writelane_b32 v252, s2, 50
	s_nop 1
	v_writelane_b32 v252, s3, 51
	s_add_u32 s2, s20, 0x40080
	v_writelane_b32 v252, s20, 52
	s_addc_u32 s3, s21, 0
	s_nop 0
	v_writelane_b32 v252, s21, 53
	v_writelane_b32 v252, s2, 54
	s_nop 1
	v_writelane_b32 v252, s3, 55
	s_add_u32 s2, s54, 64
	s_addc_u32 s3, s55, 0
	v_writelane_b32 v252, s2, 56
	s_mov_b64 s[60:61], s[52:53]
	s_mov_b64 s[58:59], s[50:51]
	v_writelane_b32 v252, s3, 57
	s_add_u32 s2, s48, 0x1810
	v_writelane_b32 v252, s2, 58
	s_addc_u32 s2, s49, 0
	v_writelane_b32 v252, s2, 59
	s_lshl_b32 s2, s26, 2
	v_writelane_b32 v252, s2, 60
	s_lshl_b32 s2, s28, 2
	v_writelane_b32 v252, s2, 61
	s_add_u32 s2, s48, 0xc730
	v_writelane_b32 v252, s2, 62
	s_addc_u32 s2, s49, 0
	v_writelane_b32 v252, s2, 63
	s_add_u32 s2, s48, 0x17650
	v_writelane_b32 v253, s2, 0
	s_addc_u32 s2, s49, 0
	v_writelane_b32 v253, s2, 1
	s_add_u32 s2, s48, 0x22570
	v_writelane_b32 v253, s2, 2
	s_mov_b64 s[56:57], s[48:49]
	s_mov_b64 s[54:55], s[46:47]
	s_mov_b64 s[52:53], s[44:45]
	v_writelane_b32 v253, s52, 3
	s_addc_u32 s2, s49, 0
	s_load_dwordx16 s[36:51], s[0:1], 0x40
	v_writelane_b32 v253, s53, 4
	v_writelane_b32 v253, s54, 5
	v_writelane_b32 v253, s55, 6
	v_writelane_b32 v253, s56, 7
	v_writelane_b32 v253, s57, 8
	v_writelane_b32 v253, s58, 9
	v_writelane_b32 v253, s59, 10
	v_writelane_b32 v253, s60, 11
	v_writelane_b32 v253, s61, 12
	v_writelane_b32 v253, s62, 13
	v_writelane_b32 v253, s63, 14
	v_writelane_b32 v253, s64, 15
	v_writelane_b32 v253, s65, 16
	v_writelane_b32 v253, s66, 17
	v_writelane_b32 v253, s67, 18
	v_writelane_b32 v253, s2, 19
	s_add_u32 s2, s12, 0x400
	s_addc_u32 s3, s13, 0
	v_writelane_b32 v253, s2, 20
	s_waitcnt lgkmcnt(0)
	s_add_u32 s0, s50, 0xc00
	v_writelane_b32 v253, s3, 21
	v_writelane_b32 v253, s36, 22
	s_addc_u32 s1, s51, 0
	s_ashr_i32 s83, s82, 31
	v_writelane_b32 v253, s37, 23
	v_writelane_b32 v253, s38, 24
	v_writelane_b32 v253, s39, 25
	v_writelane_b32 v253, s40, 26
	v_writelane_b32 v253, s41, 27
	v_writelane_b32 v253, s42, 28
	v_writelane_b32 v253, s43, 29
	v_writelane_b32 v253, s44, 30
	v_writelane_b32 v253, s45, 31
	v_writelane_b32 v253, s46, 32
	v_writelane_b32 v253, s47, 33
	v_writelane_b32 v253, s48, 34
	v_writelane_b32 v253, s49, 35
	v_writelane_b32 v253, s50, 36
	v_writelane_b32 v253, s51, 37
	v_writelane_b32 v253, s0, 38
	s_lshl_b64 s[88:89], s[82:83], 12
	s_mov_b64 s[2:3], 0x80
	v_writelane_b32 v253, s1, 39
	s_add_i32 s0, 0, 0x202c0
	v_writelane_b32 v253, s0, 40
	s_add_i32 s0, 0, 0x24000
	v_writelane_b32 v253, s0, 41
	s_add_i32 s0, 0, 0x24004
	v_writelane_b32 v253, s0, 42
	v_cmp_eq_u32_e64 s[0:1], 0, v0
	s_mov_b32 s36, 0x3e0293ee
	s_nop 0
	v_writelane_b32 v253, s0, 43
	s_nop 1
	v_writelane_b32 v253, s1, 44
	s_mov_b32 s0, s82
	v_writelane_b32 v253, s0, 45
	s_nop 1
	v_writelane_b32 v253, s1, 46
	v_writelane_b32 v253, s88, 47
	s_nop 1
	v_writelane_b32 v253, s89, 48
	s_branch .LBB0_11

;     __device__ bool next(int i, Unit& u) const { const int tile = c + (i >> 2) * G; if (tile >= ntile) return false; u.pm = tile >> 2; u.pn = (i & 3) * 4 + (tile & 3); return true; }
;     __device__ bool next(int i, Unit& u) const {
;         const long L = (long)i * G + c; if (L >= nwg) return false;
;         int wgid = (int)L; { const int q = nwg / NXCD, r = nwg % NXCD, xcd = wgid % NXCD, off = wgid / NXCD; wgid = (xcd < r ? xcd * (q + 1) : r * (q + 1) + (xcd - r) * q) + off; }
;         const int nig = WGM * nN, gid = wgid / nig, fm = gid * WGM, gsz = (nM - fm) < WGM ? (nM - fm) : WGM;
;         u.pm = fm + ((wgid % nig) % gsz); u.pn = (wgid % nig) / gsz;
;         if (nN == 44) u.pn = (u.pn + 5 * (int)(L % NXCD)) % 44;
.LBB0_1042:
	s_add_i32 s50, s50, 1
	v_readlane_b32 s22, v251, 35
	v_readlane_b32 s38, v251, 9
	s_mul_i32 s22, s50, s22
	s_mul_hi_u32 s23, s50, s38
	s_add_i32 s23, s23, s22
	s_mul_i32 s22, s50, s38
	v_readlane_b32 s38, v251, 0
	s_add_u32 s22, s22, s38
	v_readlane_b32 s38, v251, 34
	v_readlane_b32 s39, v251, 10
	s_addc_u32 s23, s23, s38
	v_cmp_gt_i64_e64 s[38:39], s[22:23], v[164:165]
	s_and_b64 vcc, exec, s[38:39]
	s_cbranch_vccnz .LBB0_1044
	s_ashr_i32 s40, s22, 31
	s_lshr_b32 s40, s40, 29
	s_add_i32 s40, s22, s40
	s_ashr_i32 s41, s40, 3
	s_and_b32 s40, s40, -8
	s_sub_i32 s40, s22, s40
	s_cmp_lt_i32 s40, 0
	s_movk_i32 s42, 0x161
	s_cselect_b32 s42, s42, 0x160
	s_mul_i32 s40, s42, s40
	s_add_i32 s40, s40, s41
	s_mul_hi_i32 s41, s40, 0x2e8ba2e9
	s_lshr_b32 s42, s41, 31
	s_ashr_i32 s41, s41, 5
	s_add_i32 s41, s41, s42
	s_lshl_b32 s42, s41, 2
	s_sub_i32 s43, 64, s42
	s_min_i32 s43, s43, 4
	s_abs_i32 s46, s43
	v_cvt_f32_u32_e32 v0, s46
	s_sub_i32 s48, 0, s46
	s_mulk_i32 s41, 0xb0
	s_sub_i32 s40, s40, s41
	v_rcp_iflag_f32_e32 v0, v0
	s_abs_i32 s41, s40
	s_xor_b32 s47, s40, s43
	s_ashr_i32 s47, s47, 31
	v_mul_f32_e32 v0, 0x4f7ffffe, v0
	v_cvt_u32_f32_e32 v0, v0
	s_nop 0
	v_readfirstlane_b32 s49, v0
	s_mul_i32 s48, s48, s49
	s_mul_hi_u32 s48, s49, s48
	s_add_i32 s49, s49, s48
	s_mul_hi_u32 s48, s41, s49
	s_mul_i32 s49, s48, s46
	s_sub_i32 s41, s41, s49
	s_add_i32 s52, s48, 1
	s_sub_i32 s49, s41, s46
	s_cmp_ge_u32 s41, s46
	s_cselect_b32 s48, s52, s48
	s_cselect_b32 s41, s49, s41
	s_add_i32 s49, s48, 1
	s_cmp_ge_u32 s41, s46
	s_cselect_b32 s41, s49, s48
	s_xor_b32 s41, s41, s47
	s_sub_i32 s41, s41, s47
	s_mul_i32 s43, s41, s43
	s_sub_i32 s40, s40, s43
	s_add_i32 s40, s40, s42
	s_ashr_i32 s42, s23, 31
	s_lshr_b32 s42, s42, 29
	s_add_i32 s42, s22, s42
	s_and_b32 s42, s42, -8
	s_sub_i32 s42, s22, s42
	s_mul_i32 s42, s42, 11
	s_add_i32 s41, s41, s42
	s_mul_i32 s42, s41, 0xba3
	s_lshr_b32 s43, s42, 31
	s_lshr_b32 s42, s42, 17
	s_add_i32 s42, s42, s43
	s_mul_i32 s42, s42, 44
	s_sub_i32 s41, s41, s42
	s_sext_i32_i16 s42, s41
